# v28 + branch-GEMM: removed hipcc's full vmcnt(0) drain at each z-unit start (the loop's counted waits retire the gate loads, as the source intends)
# speedup vs baseline: 1.0020x; 1.0020x over previous
; #define PG8_STAGE(bufoff, gbase, voff) do { _Pragma("unroll") for (int _i = 0; _i < 2; ++_i) \
;         __builtin_amdgcn_global_load_lds((const unsigned*)((const char*)(gbase) + (voff)[_i]), (LAS unsigned*)(lds + (bufoff) + ldsw + _i * 8192), 16, 0, 0); } while (0)
; #define PG8_LDA(dst, b, h) do { _Pragma("unroll") for (int m = 0; m < 4; ++m) _Pragma("unroll") for (int k = 0; k < 2; ++k) dst[m][k] = *(const LAS bf16x8*)(lds + PG8_SA(b, h) + aoff + m * 2048 + k * 1024); } while (0)
; #define PG8_LDB(dst, b, h) do { _Pragma("unroll") for (int n = 0; n < 2; ++n) _Pragma("unroll") for (int k = 0; k < 2; ++k) dst[n][k] = *(const LAS bf16x8*)(lds + PG8_SB(b, h) + boff + n * 2048 + k * 1024); } while (0)
; #define PG8_WAIT_V(n) asm volatile("s_waitcnt vmcnt(" #n ")" ::: "memory")
; #define PG8_WAIT_L(n) asm volatile("s_waitcnt lgkmcnt(" #n ")" ::: "memory")
; template <class Epi, class Sched, bool HALFN = false>
; __device__ __forceinline__ void gemm_phase(LAS unsigned char* lds, const Gemm g, const Sched& S, const Epi& E, int wave_s) {
;     ...
;     for (;;) {
;         const bool has_next = S.next(ui + 1, nxt);
;         const char* nA = has_next ? (const char*)g.A + (size_t)nxt.z * g.zA * 2 + (size_t)nxt.pm * tstep : cA; const char* nB = has_next ? (const char*)g.Bt + (size_t)nxt.z * g.zB * 2 + (size_t)nxt.pn * (HALFN ? hstep : tstep) : cB;
;         for (int t = 0; t < nt; t += 2) {
;             const bool last = (t == nt - 2);
;             const char* a1 = cA + (size_t)(t + 1) * kstep;
;             const char* a2 = last ? nA : cA + (size_t)(t + 2) * kstep; const char* b2 = last ? nB : cB + (size_t)(t + 2) * kstep;
;             const char* a3 = a2 + kstep; const char* b3 = b2 + kstep;
;             PG8_LDB(B0, 0, 0); if (!HALFN) PG8_LDB(B1, 0, 1); PG8_SCHED; PG8_LDA(At, 0, 0); PG8_STAGE(PG8_SA(1, 1), a1 + hstep, voffA);
;             PG8_WAIT_V(8); PG8_WAIT_L(0); PG8_BAR; PG8_MMA(0, 0, At, B0); if (!HALFN) PG8_MMA(0, 1, At, B1); PG8_BAR; PG8_SCHED;
;             PG8_LDA(At, 0, 1); PG8_STAGE(PG8_SB(0, 0), b2, voffB); PG8_STAGE(PG8_SB(0, 1), b2 + bh1, voffB); PG8_STAGE(PG8_SA(0, 0), a2, voffA);
;             PG8_WAIT_V(8); PG8_WAIT_L(0); PG8_BAR; PG8_MMA(1, 0, At, B0); if (!HALFN) PG8_MMA(1, 1, At, B1); PG8_BAR; PG8_SCHED;
;             PG8_LDB(B0, 1, 0); if (!HALFN) PG8_LDB(B1, 1, 1); PG8_SCHED; PG8_LDA(At, 1, 0); PG8_STAGE(PG8_SA(0, 1), a2 + hstep, voffA);
.LBB0_890:
	s_lshl_b64 s[26:27], s[48:49], 20
	s_add_u32 s23, s38, s26
	s_addc_u32 s29, s39, s27
	s_ashr_i32 s21, s20, 31
	s_lshl_b64 s[26:27], s[20:21], 17
	s_add_u32 s26, s23, s26
	s_addc_u32 s27, s29, s27
	s_and_b64 s[4:5], s[4:5], exec
	s_cselect_b32 s5, s27, s37
	s_cselect_b32 s4, s26, s36
	s_add_i32 s48, 0, 0x10000
	v_add_u32_e32 v44, s48, v1
	ds_read_b128 v[46:49], v44
	ds_read_b128 v[50:53], v44 offset:1024
	ds_read_b128 v[54:57], v44 offset:2048
	ds_read_b128 v[58:61], v44 offset:3072
	s_add_u32 s74, s34, 0x20080
	s_addc_u32 s75, s35, 0
	s_add_i32 s52, s31, 0xc000
	v_lshl_add_u64 v[86:87], s[74:75], 0, v[100:101]
	s_mov_b32 m0, s52
	s_add_i32 s21, s31, 0xe000
	ds_read_b128 v[36:39], v176
	ds_read_b128 v[40:43], v176 offset:1024
	ds_read_b128 v[62:65], v176 offset:2048
	ds_read_b128 v[66:69], v176 offset:3072
	ds_read_b128 v[70:73], v176 offset:4096
	ds_read_b128 v[74:77], v176 offset:5120
	ds_read_b128 v[78:81], v176 offset:6144
	ds_read_b128 v[82:85], v176 offset:7168
	global_load_lds_dwordx4 v[86:87], off
	v_lshl_add_u64 v[86:87], s[74:75], 0, v[102:103]
	s_mov_b32 m0, s21
	s_nop 0
	global_load_lds_dwordx4 v[86:87], off
	s_waitcnt vmcnt(8)
	s_waitcnt lgkmcnt(0)
	s_barrier
	s_setprio 1
	s_waitcnt lgkmcnt(0)
	v_mfma_f32_16x16x32_bf16 v[86:89], v[46:49], v[36:39], 0
	v_mfma_f32_16x16x32_bf16 v[36:39], v[54:57], v[36:39], 0
	v_mfma_f32_16x16x32_bf16 v[90:93], v[58:61], v[40:43], v[36:39]
	v_mfma_f32_16x16x32_bf16 v[36:39], v[46:49], v[62:65], 0
	v_mfma_f32_16x16x32_bf16 v[94:97], v[50:53], v[66:69], v[36:39]
	v_mfma_f32_16x16x32_bf16 v[36:39], v[54:57], v[62:65], 0
	v_mfma_f32_16x16x32_bf16 v[62:65], v[58:61], v[66:69], v[36:39]
	v_mfma_f32_16x16x32_bf16 v[36:39], v[46:49], v[70:73], 0
	v_mfma_f32_16x16x32_bf16 v[66:69], v[50:53], v[74:77], v[36:39]
	v_mfma_f32_16x16x32_bf16 v[36:39], v[54:57], v[70:73], 0
	v_mfma_f32_16x16x32_bf16 v[70:73], v[58:61], v[74:77], v[36:39]
	v_mfma_f32_16x16x32_bf16 v[36:39], v[46:49], v[78:81], 0
	v_mfma_f32_16x16x32_bf16 v[74:77], v[50:53], v[82:85], v[36:39]
	v_mfma_f32_16x16x32_bf16 v[36:39], v[54:57], v[78:81], 0
	v_mfma_f32_16x16x32_bf16 v[86:89], v[50:53], v[40:43], v[86:89]
	v_mfma_f32_16x16x32_bf16 v[78:81], v[58:61], v[82:85], v[36:39]
	s_setprio 0
	s_barrier
	s_nop 3
	v_lshl_add_u64 v[36:37], s[36:37], 0, v[18:19]
	s_mov_b64 s[74:75], 0x100
	s_add_i32 s48, s48, s41
	v_lshl_add_u64 v[40:41], v[36:37], 0, s[74:75]
	s_mov_b32 m0, s48
	v_lshl_add_u64 v[38:39], s[36:37], 0, v[104:105]
	s_add_i32 s23, s48, 0x2000
	ds_read_b128 v[82:85], v176 offset:16384
	ds_read_b128 v[170:173], v176 offset:17408
	ds_read_b128 v[178:181], v176 offset:18432
	ds_read_b128 v[182:185], v176 offset:19456
	ds_read_b128 v[186:189], v176 offset:20480
	ds_read_b128 v[190:193], v176 offset:21504
	ds_read_b128 v[194:197], v176 offset:22528
	ds_read_b128 v[208:211], v176 offset:23552
	global_load_lds_dwordx4 v[40:41], off
	v_lshl_add_u64 v[42:43], v[38:39], 0, s[74:75]
	s_mov_b32 m0, s23
	s_nop 0
	global_load_lds_dwordx4 v[42:43], off
	s_mov_b32 m0, s47
	s_nop 0
	global_load_lds_dwordx4 v[40:41], off
	s_mov_b32 m0, s55
	v_lshl_add_u64 v[40:41], s[34:35], 0, v[100:101]
	global_load_lds_dwordx4 v[42:43], off
	v_lshl_add_u64 v[42:43], v[40:41], 0, s[74:75]
	s_mov_b32 m0, s31
	s_nop 0
	global_load_lds_dwordx4 v[42:43], off
	v_lshl_add_u64 v[42:43], s[34:35], 0, v[102:103]
	v_lshl_add_u64 v[98:99], v[42:43], 0, s[74:75]
	s_mov_b32 m0, s56
	s_nop 0
	global_load_lds_dwordx4 v[98:99], off
	s_waitcnt vmcnt(8)
	s_waitcnt lgkmcnt(0)
	s_barrier
	s_setprio 1
	s_waitcnt lgkmcnt(0)
	v_mfma_f32_16x16x32_bf16 v[212:215], v[46:49], v[82:85], 0
	v_mfma_f32_16x16x32_bf16 v[82:85], v[54:57], v[82:85], 0
	v_mfma_f32_16x16x32_bf16 v[212:215], v[50:53], v[170:173], v[212:215]
	v_mfma_f32_16x16x32_bf16 v[82:85], v[58:61], v[170:173], v[82:85]
	v_mfma_f32_16x16x32_bf16 v[170:173], v[46:49], v[178:181], 0
	v_mfma_f32_16x16x32_bf16 v[178:181], v[54:57], v[178:181], 0
	v_mfma_f32_16x16x32_bf16 v[170:173], v[50:53], v[182:185], v[170:173]
	v_mfma_f32_16x16x32_bf16 v[178:181], v[58:61], v[182:185], v[178:181]
	v_mfma_f32_16x16x32_bf16 v[182:185], v[46:49], v[186:189], 0
	v_mfma_f32_16x16x32_bf16 v[46:49], v[46:49], v[194:197], 0
	v_mfma_f32_16x16x32_bf16 v[182:185], v[50:53], v[190:193], v[182:185]
	v_mfma_f32_16x16x32_bf16 v[46:49], v[50:53], v[208:211], v[46:49]
	v_mfma_f32_16x16x32_bf16 v[50:53], v[54:57], v[194:197], 0
	v_mfma_f32_16x16x32_bf16 v[186:189], v[54:57], v[186:189], 0
	v_mfma_f32_16x16x32_bf16 v[50:53], v[58:61], v[208:211], v[50:53]
	v_mfma_f32_16x16x32_bf16 v[186:189], v[58:61], v[190:193], v[186:189]
	s_setprio 0
	s_barrier
	s_add_i32 s29, 0, 0x18000
	v_add_u32_e32 v45, s29, v1
	ds_read_b128 v[54:57], v45
	ds_read_b128 v[58:61], v45 offset:1024
	ds_read_b128 v[190:193], v45 offset:2048
	ds_read_b128 v[194:197], v45 offset:3072
	s_add_u32 s36, s34, 0x20100
	s_addc_u32 s37, s35, 0
	s_mov_b32 m0, s57
	v_lshl_add_u64 v[98:99], s[36:37], 0, v[100:101]
	ds_read_b128 v[208:211], v176 offset:32768
	ds_read_b128 v[216:219], v176 offset:33792
	ds_read_b128 v[220:223], v176 offset:34816
	ds_read_b128 v[224:227], v176 offset:35840
	ds_read_b128 v[228:231], v176 offset:36864
	ds_read_b128 v[232:235], v176 offset:37888
	ds_read_b128 v[236:239], v176 offset:38912
	ds_read_b128 v[240:243], v176 offset:39936
	global_load_lds_dwordx4 v[98:99], off
	v_lshl_add_u64 v[98:99], s[36:37], 0, v[102:103]
	s_mov_b32 m0, s58
	s_nop 0
	global_load_lds_dwordx4 v[98:99], off
	s_waitcnt vmcnt(8)
	s_waitcnt lgkmcnt(0)
	s_barrier
; #define PG8_STAGE(bufoff, gbase, voff) do { _Pragma("unroll") for (int _i = 0; _i < 2; ++_i) \
;         __builtin_amdgcn_global_load_lds((const unsigned*)((const char*)(gbase) + (voff)[_i]), (LAS unsigned*)(lds + (bufoff) + ldsw + _i * 8192), 16, 0, 0); } while (0)
; #define PG8_LDA(dst, b, h) do { _Pragma("unroll") for (int m = 0; m < 4; ++m) _Pragma("unroll") for (int k = 0; k < 2; ++k) dst[m][k] = *(const LAS bf16x8*)(lds + PG8_SA(b, h) + aoff + m * 2048 + k * 1024); } while (0)
; #define PG8_LDB(dst, b, h) do { _Pragma("unroll") for (int n = 0; n < 2; ++n) _Pragma("unroll") for (int k = 0; k < 2; ++k) dst[n][k] = *(const LAS bf16x8*)(lds + PG8_SB(b, h) + boff + n * 2048 + k * 1024); } while (0)
; #define PG8_MMA(ai, bj, At, Bt) do { __builtin_amdgcn_s_setprio(1); _Pragma("unroll") for (int m = 0; m < 4; ++m) _Pragma("unroll") for (int n = 0; n < 2; ++n) _Pragma("unroll") for (int k = 0; k < 2; ++k) \
;         acc[ai][bj][m][n] = __builtin_amdgcn_mfma_f32_16x16x32_bf16(Bt[n][k], At[m][k], acc[ai][bj][m][n], 0, 0, 0); __builtin_amdgcn_s_setprio(0); } while (0)
; #define PG8_WAIT_V(n) asm volatile("s_waitcnt vmcnt(" #n ")" ::: "memory")
; #define PG8_WAIT_L(n) asm volatile("s_waitcnt lgkmcnt(" #n ")" ::: "memory")
; #define PG8_BAR __builtin_amdgcn_s_barrier()
; #define PG8_SCHED __builtin_amdgcn_sched_barrier(0)
; template <class Epi, class Sched, bool HALFN = false>
; __device__ __forceinline__ void gemm_phase(LAS unsigned char* lds, const Gemm g, const Sched& S, const Epi& E, int wave_s) {
;     ...
;             PG8_LDB(B0, 1, 0); if (!HALFN) PG8_LDB(B1, 1, 1); PG8_SCHED; PG8_LDA(At, 1, 0); PG8_STAGE(PG8_SA(0, 1), a2 + hstep, voffA);
;             PG8_WAIT_V(8); PG8_WAIT_L(0); PG8_BAR; PG8_MMA(0, 0, At, B0); if (!HALFN) PG8_MMA(0, 1, At, B1); PG8_BAR; PG8_SCHED;
;             PG8_LDA(At, 1, 1); PG8_STAGE(PG8_SB(1, 0), b3, voffB); PG8_STAGE(PG8_SB(1, 1), b3 + bh1, voffB); PG8_STAGE(PG8_SA(1, 0), a3, voffA);
;             PG8_WAIT_V(8); PG8_WAIT_L(0); PG8_BAR; PG8_MMA(1, 0, At, B0); if (!HALFN) PG8_MMA(1, 1, At, B1); PG8_BAR; PG8_SCHED;
	s_setprio 1
	s_waitcnt lgkmcnt(0)
	v_mfma_f32_16x16x32_bf16 v[86:89], v[54:57], v[208:211], v[86:89]
	v_mfma_f32_16x16x32_bf16 v[90:93], v[190:193], v[208:211], v[90:93]
	v_mfma_f32_16x16x32_bf16 v[94:97], v[54:57], v[220:223], v[94:97]
	v_mfma_f32_16x16x32_bf16 v[62:65], v[190:193], v[220:223], v[62:65]
	v_mfma_f32_16x16x32_bf16 v[66:69], v[54:57], v[228:231], v[66:69]
	v_mfma_f32_16x16x32_bf16 v[70:73], v[190:193], v[228:231], v[70:73]
	v_mfma_f32_16x16x32_bf16 v[74:77], v[54:57], v[236:239], v[74:77]
	v_mfma_f32_16x16x32_bf16 v[78:81], v[190:193], v[236:239], v[78:81]
	v_mfma_f32_16x16x32_bf16 v[86:89], v[58:61], v[216:219], v[86:89]
	v_mfma_f32_16x16x32_bf16 v[90:93], v[194:197], v[216:219], v[90:93]
	v_mfma_f32_16x16x32_bf16 v[94:97], v[58:61], v[224:227], v[94:97]
	v_mfma_f32_16x16x32_bf16 v[62:65], v[194:197], v[224:227], v[62:65]
	v_mfma_f32_16x16x32_bf16 v[66:69], v[58:61], v[232:235], v[66:69]
	v_mfma_f32_16x16x32_bf16 v[70:73], v[194:197], v[232:235], v[70:73]
	v_mfma_f32_16x16x32_bf16 v[74:77], v[58:61], v[240:243], v[74:77]
	v_mfma_f32_16x16x32_bf16 v[78:81], v[194:197], v[240:243], v[78:81]
	s_setprio 0
	s_barrier
	s_mov_b64 s[74:75], 0x180
	s_add_i32 s36, s29, s41
	v_lshl_add_u64 v[98:99], v[36:37], 0, s[74:75]
	s_mov_b32 m0, s36
	s_add_i32 s29, s36, 0x2000
	ds_read_b128 v[208:211], v176 offset:49152
	ds_read_b128 v[216:219], v176 offset:50176
	ds_read_b128 v[220:223], v176 offset:51200
	ds_read_b128 v[224:227], v176 offset:52224
	ds_read_b128 v[228:231], v176 offset:53248
	ds_read_b128 v[232:235], v176 offset:54272
	ds_read_b128 v[236:239], v176 offset:55296
	ds_read_b128 v[240:243], v176 offset:56320
	global_load_lds_dwordx4 v[98:99], off
	v_lshl_add_u64 v[174:175], v[38:39], 0, s[74:75]
	s_mov_b32 m0, s29
	s_nop 0
	global_load_lds_dwordx4 v[174:175], off
	s_mov_b32 m0, s64
	s_nop 0
	global_load_lds_dwordx4 v[98:99], off
	s_mov_b32 m0, s65
	v_lshl_add_u64 v[98:99], v[40:41], 0, s[74:75]
	global_load_lds_dwordx4 v[174:175], off
	s_mov_b32 m0, s59
	s_nop 0
	global_load_lds_dwordx4 v[98:99], off
	v_lshl_add_u64 v[98:99], v[42:43], 0, s[74:75]
	s_mov_b32 m0, s62
	s_nop 0
	global_load_lds_dwordx4 v[98:99], off
	s_waitcnt vmcnt(8)
	s_waitcnt lgkmcnt(0)
	s_barrier
	s_setprio 1
	s_waitcnt lgkmcnt(0)
	v_mfma_f32_16x16x32_bf16 v[82:85], v[190:193], v[208:211], v[82:85]
	v_mfma_f32_16x16x32_bf16 v[46:49], v[54:57], v[236:239], v[46:49]
	v_mfma_f32_16x16x32_bf16 v[50:53], v[190:193], v[236:239], v[50:53]
	v_mfma_f32_16x16x32_bf16 v[212:215], v[54:57], v[208:211], v[212:215]
	v_mfma_f32_16x16x32_bf16 v[82:85], v[194:197], v[216:219], v[82:85]
	v_mfma_f32_16x16x32_bf16 v[170:173], v[54:57], v[220:223], v[170:173]
	v_mfma_f32_16x16x32_bf16 v[178:181], v[190:193], v[220:223], v[178:181]
	v_mfma_f32_16x16x32_bf16 v[182:185], v[54:57], v[228:231], v[182:185]
	v_mfma_f32_16x16x32_bf16 v[186:189], v[190:193], v[228:231], v[186:189]
	v_mfma_f32_16x16x32_bf16 v[46:49], v[58:61], v[240:243], v[46:49]
	v_mfma_f32_16x16x32_bf16 v[50:53], v[194:197], v[240:243], v[50:53]
	v_mfma_f32_16x16x32_bf16 v[212:215], v[58:61], v[216:219], v[212:215]
	v_mfma_f32_16x16x32_bf16 v[170:173], v[58:61], v[224:227], v[170:173]
	v_mfma_f32_16x16x32_bf16 v[178:181], v[194:197], v[224:227], v[178:181]
	v_mfma_f32_16x16x32_bf16 v[182:185], v[58:61], v[232:235], v[182:185]
	v_mfma_f32_16x16x32_bf16 v[186:189], v[194:197], v[232:235], v[186:189]
	s_setprio 0
	s_barrier
	ds_read_b128 v[54:57], v44
	ds_read_b128 v[58:61], v44 offset:1024
	ds_read_b128 v[190:193], v44 offset:2048
	ds_read_b128 v[194:197], v44 offset:3072
	s_add_u32 s74, s34, 0x20180
	s_addc_u32 s75, s35, 0
	s_mov_b32 m0, s52
	v_lshl_add_u64 v[98:99], s[74:75], 0, v[100:101]
	ds_read_b128 v[208:211], v176
	ds_read_b128 v[216:219], v176 offset:1024
	ds_read_b128 v[220:223], v176 offset:2048
	ds_read_b128 v[224:227], v176 offset:3072
	ds_read_b128 v[228:231], v176 offset:4096
	ds_read_b128 v[232:235], v176 offset:5120
	ds_read_b128 v[236:239], v176 offset:6144
	ds_read_b128 v[240:243], v176 offset:7168
	global_load_lds_dwordx4 v[98:99], off
	v_lshl_add_u64 v[98:99], s[74:75], 0, v[102:103]
	s_mov_b32 m0, s21
	s_nop 0
	global_load_lds_dwordx4 v[98:99], off
	s_waitcnt vmcnt(8)
	s_waitcnt lgkmcnt(0)
	s_barrier
	s_setprio 1
	s_waitcnt lgkmcnt(0)
	v_mfma_f32_16x16x32_bf16 v[86:89], v[54:57], v[208:211], v[86:89]
	v_mfma_f32_16x16x32_bf16 v[90:93], v[190:193], v[208:211], v[90:93]
	v_mfma_f32_16x16x32_bf16 v[94:97], v[54:57], v[220:223], v[94:97]
	v_mfma_f32_16x16x32_bf16 v[62:65], v[190:193], v[220:223], v[62:65]
	v_mfma_f32_16x16x32_bf16 v[66:69], v[54:57], v[228:231], v[66:69]
	v_mfma_f32_16x16x32_bf16 v[70:73], v[190:193], v[228:231], v[70:73]
	v_mfma_f32_16x16x32_bf16 v[74:77], v[54:57], v[236:239], v[74:77]
	v_mfma_f32_16x16x32_bf16 v[78:81], v[190:193], v[236:239], v[78:81]
	v_mfma_f32_16x16x32_bf16 v[86:89], v[58:61], v[216:219], v[86:89]
	v_mfma_f32_16x16x32_bf16 v[90:93], v[194:197], v[216:219], v[90:93]
	v_mfma_f32_16x16x32_bf16 v[94:97], v[58:61], v[224:227], v[94:97]
	v_mfma_f32_16x16x32_bf16 v[62:65], v[194:197], v[224:227], v[62:65]
	v_mfma_f32_16x16x32_bf16 v[66:69], v[58:61], v[232:235], v[66:69]
	v_mfma_f32_16x16x32_bf16 v[70:73], v[194:197], v[232:235], v[70:73]
	v_mfma_f32_16x16x32_bf16 v[74:77], v[58:61], v[240:243], v[74:77]
	v_mfma_f32_16x16x32_bf16 v[78:81], v[194:197], v[240:243], v[78:81]
	s_setprio 0
	s_barrier
; #define PG8_STAGE(bufoff, gbase, voff) do { _Pragma("unroll") for (int _i = 0; _i < 2; ++_i) \
;         __builtin_amdgcn_global_load_lds((const unsigned*)((const char*)(gbase) + (voff)[_i]), (LAS unsigned*)(lds + (bufoff) + ldsw + _i * 8192), 16, 0, 0); } while (0)
; #define PG8_LDA(dst, b, h) do { _Pragma("unroll") for (int m = 0; m < 4; ++m) _Pragma("unroll") for (int k = 0; k < 2; ++k) dst[m][k] = *(const LAS bf16x8*)(lds + PG8_SA(b, h) + aoff + m * 2048 + k * 1024); } while (0)
; #define PG8_LDB(dst, b, h) do { _Pragma("unroll") for (int n = 0; n < 2; ++n) _Pragma("unroll") for (int k = 0; k < 2; ++k) dst[n][k] = *(const LAS bf16x8*)(lds + PG8_SB(b, h) + boff + n * 2048 + k * 1024); } while (0)
; #define PG8_MMA(ai, bj, At, Bt) do { __builtin_amdgcn_s_setprio(1); _Pragma("unroll") for (int m = 0; m < 4; ++m) _Pragma("unroll") for (int n = 0; n < 2; ++n) _Pragma("unroll") for (int k = 0; k < 2; ++k) \
;         acc[ai][bj][m][n] = __builtin_amdgcn_mfma_f32_16x16x32_bf16(Bt[n][k], At[m][k], acc[ai][bj][m][n], 0, 0, 0); __builtin_amdgcn_s_setprio(0); } while (0)
; template <class Epi, class Sched, bool HALFN = false>
; __device__ __forceinline__ void gemm_phase(LAS unsigned char* lds, const Gemm g, const Sched& S, const Epi& E, int wave_s) {
;     ...
;             PG8_LDB(B0, 0, 0); if (!HALFN) PG8_LDB(B1, 0, 1); PG8_SCHED; PG8_LDA(At, 0, 0); PG8_STAGE(PG8_SA(1, 1), a1 + hstep, voffA);
;             PG8_WAIT_V(8); PG8_WAIT_L(0); PG8_BAR; PG8_MMA(0, 0, At, B0); if (!HALFN) PG8_MMA(0, 1, At, B1); PG8_BAR; PG8_SCHED;
;             PG8_LDA(At, 0, 1); PG8_STAGE(PG8_SB(0, 0), b2, voffB); PG8_STAGE(PG8_SB(0, 1), b2 + bh1, voffB); PG8_STAGE(PG8_SA(0, 0), a2, voffA);
;             PG8_WAIT_V(8); PG8_WAIT_L(0); PG8_BAR; PG8_MMA(1, 0, At, B0); if (!HALFN) PG8_MMA(1, 1, At, B1); PG8_BAR; PG8_SCHED;
;             PG8_LDB(B0, 1, 0); if (!HALFN) PG8_LDB(B1, 1, 1); PG8_SCHED; PG8_LDA(At, 1, 0); PG8_STAGE(PG8_SA(0, 1), a2 + hstep, voffA);
;             PG8_WAIT_V(8); PG8_WAIT_L(0); PG8_BAR; PG8_MMA(0, 0, At, B0); if (!HALFN) PG8_MMA(0, 1, At, B1); PG8_BAR; PG8_SCHED;
;             PG8_LDA(At, 1, 1); PG8_STAGE(PG8_SB(1, 0), b3, voffB); PG8_STAGE(PG8_SB(1, 1), b3 + bh1, voffB); PG8_STAGE(PG8_SA(1, 0), a3, voffA);
;             PG8_WAIT_V(8); PG8_WAIT_L(0); PG8_BAR; PG8_MMA(1, 0, At, B0); if (!HALFN) PG8_MMA(1, 1, At, B1); PG8_BAR; PG8_SCHED;
	s_mov_b64 s[74:75], 0x200
	s_mov_b32 m0, s48
	v_lshl_add_u64 v[98:99], v[36:37], 0, s[74:75]
	ds_read_b128 v[208:211], v176 offset:16384
	ds_read_b128 v[216:219], v176 offset:17408
	ds_read_b128 v[220:223], v176 offset:18432
	ds_read_b128 v[224:227], v176 offset:19456
	ds_read_b128 v[228:231], v176 offset:20480
	ds_read_b128 v[232:235], v176 offset:21504
	ds_read_b128 v[236:239], v176 offset:22528
	ds_read_b128 v[240:243], v176 offset:23552
	global_load_lds_dwordx4 v[98:99], off
	v_lshl_add_u64 v[174:175], v[38:39], 0, s[74:75]
	s_mov_b32 m0, s23
	s_nop 0
	global_load_lds_dwordx4 v[174:175], off
	s_mov_b32 m0, s47
	s_nop 0
	global_load_lds_dwordx4 v[98:99], off
	s_mov_b32 m0, s55
	v_lshl_add_u64 v[98:99], v[40:41], 0, s[74:75]
	global_load_lds_dwordx4 v[174:175], off
	s_mov_b32 m0, s31
	s_nop 0
	global_load_lds_dwordx4 v[98:99], off
	v_lshl_add_u64 v[98:99], v[42:43], 0, s[74:75]
	s_mov_b32 m0, s56
	s_nop 0
	global_load_lds_dwordx4 v[98:99], off
	s_waitcnt vmcnt(8)
	s_waitcnt lgkmcnt(0)
	s_barrier
	s_setprio 1
	s_waitcnt lgkmcnt(0)
	v_mfma_f32_16x16x32_bf16 v[82:85], v[190:193], v[208:211], v[82:85]
	v_mfma_f32_16x16x32_bf16 v[46:49], v[54:57], v[236:239], v[46:49]
	v_mfma_f32_16x16x32_bf16 v[50:53], v[190:193], v[236:239], v[50:53]
	v_mfma_f32_16x16x32_bf16 v[212:215], v[54:57], v[208:211], v[212:215]
	v_mfma_f32_16x16x32_bf16 v[82:85], v[194:197], v[216:219], v[82:85]
	v_mfma_f32_16x16x32_bf16 v[170:173], v[54:57], v[220:223], v[170:173]
	v_mfma_f32_16x16x32_bf16 v[178:181], v[190:193], v[220:223], v[178:181]
	v_mfma_f32_16x16x32_bf16 v[182:185], v[54:57], v[228:231], v[182:185]
	v_mfma_f32_16x16x32_bf16 v[186:189], v[190:193], v[228:231], v[186:189]
	v_mfma_f32_16x16x32_bf16 v[46:49], v[58:61], v[240:243], v[46:49]
	v_mfma_f32_16x16x32_bf16 v[50:53], v[194:197], v[240:243], v[50:53]
	v_mfma_f32_16x16x32_bf16 v[212:215], v[58:61], v[216:219], v[212:215]
	v_mfma_f32_16x16x32_bf16 v[170:173], v[58:61], v[224:227], v[170:173]
	v_mfma_f32_16x16x32_bf16 v[178:181], v[194:197], v[224:227], v[178:181]
	v_mfma_f32_16x16x32_bf16 v[182:185], v[58:61], v[232:235], v[182:185]
	v_mfma_f32_16x16x32_bf16 v[186:189], v[194:197], v[232:235], v[186:189]
	s_setprio 0
	s_barrier
	ds_read_b128 v[54:57], v45
	ds_read_b128 v[58:61], v45 offset:1024
	ds_read_b128 v[190:193], v45 offset:2048
	ds_read_b128 v[194:197], v45 offset:3072
	s_add_u32 s74, s34, 0x20200
	s_addc_u32 s75, s35, 0
	s_mov_b32 m0, s57
	v_lshl_add_u64 v[98:99], s[74:75], 0, v[100:101]
	ds_read_b128 v[208:211], v176 offset:32768
	ds_read_b128 v[216:219], v176 offset:33792
	ds_read_b128 v[220:223], v176 offset:34816
	ds_read_b128 v[224:227], v176 offset:35840
	ds_read_b128 v[228:231], v176 offset:36864
	ds_read_b128 v[232:235], v176 offset:37888
	ds_read_b128 v[236:239], v176 offset:38912
	ds_read_b128 v[240:243], v176 offset:39936
	global_load_lds_dwordx4 v[98:99], off
	v_lshl_add_u64 v[98:99], s[74:75], 0, v[102:103]
	s_mov_b32 m0, s58
	s_nop 0
	global_load_lds_dwordx4 v[98:99], off
	s_waitcnt vmcnt(8)
	s_waitcnt lgkmcnt(0)
	s_barrier
	s_setprio 1
	s_waitcnt lgkmcnt(0)
	v_mfma_f32_16x16x32_bf16 v[86:89], v[54:57], v[208:211], v[86:89]
	v_mfma_f32_16x16x32_bf16 v[90:93], v[190:193], v[208:211], v[90:93]
	v_mfma_f32_16x16x32_bf16 v[94:97], v[54:57], v[220:223], v[94:97]
	v_mfma_f32_16x16x32_bf16 v[62:65], v[190:193], v[220:223], v[62:65]
	v_mfma_f32_16x16x32_bf16 v[66:69], v[54:57], v[228:231], v[66:69]
	v_mfma_f32_16x16x32_bf16 v[70:73], v[190:193], v[228:231], v[70:73]
	v_mfma_f32_16x16x32_bf16 v[74:77], v[54:57], v[236:239], v[74:77]
	v_mfma_f32_16x16x32_bf16 v[78:81], v[190:193], v[236:239], v[78:81]
	v_mfma_f32_16x16x32_bf16 v[86:89], v[58:61], v[216:219], v[86:89]
	v_mfma_f32_16x16x32_bf16 v[90:93], v[194:197], v[216:219], v[90:93]
	v_mfma_f32_16x16x32_bf16 v[94:97], v[58:61], v[224:227], v[94:97]
	v_mfma_f32_16x16x32_bf16 v[62:65], v[194:197], v[224:227], v[62:65]
	v_mfma_f32_16x16x32_bf16 v[66:69], v[58:61], v[232:235], v[66:69]
	v_mfma_f32_16x16x32_bf16 v[70:73], v[194:197], v[232:235], v[70:73]
	v_mfma_f32_16x16x32_bf16 v[74:77], v[58:61], v[240:243], v[74:77]
	v_mfma_f32_16x16x32_bf16 v[78:81], v[194:197], v[240:243], v[78:81]
	s_setprio 0
	s_barrier
	s_mov_b64 s[74:75], 0x280
	s_mov_b32 m0, s36
	v_lshl_add_u64 v[98:99], v[36:37], 0, s[74:75]
	ds_read_b128 v[208:211], v176 offset:49152
	ds_read_b128 v[216:219], v176 offset:50176
	ds_read_b128 v[220:223], v176 offset:51200
	ds_read_b128 v[224:227], v176 offset:52224
	ds_read_b128 v[228:231], v176 offset:53248
	ds_read_b128 v[232:235], v176 offset:54272
	ds_read_b128 v[236:239], v176 offset:55296
	ds_read_b128 v[240:243], v176 offset:56320
	global_load_lds_dwordx4 v[98:99], off
	v_lshl_add_u64 v[174:175], v[38:39], 0, s[74:75]
	s_mov_b32 m0, s29
	s_nop 0
	global_load_lds_dwordx4 v[174:175], off
	s_mov_b32 m0, s64
	s_nop 0
	global_load_lds_dwordx4 v[98:99], off
	s_mov_b32 m0, s65
	v_lshl_add_u64 v[98:99], v[40:41], 0, s[74:75]
	global_load_lds_dwordx4 v[174:175], off
	s_mov_b32 m0, s59
	s_nop 0
	global_load_lds_dwordx4 v[98:99], off
	v_lshl_add_u64 v[98:99], v[42:43], 0, s[74:75]
	s_mov_b32 m0, s62
	s_nop 0
	global_load_lds_dwordx4 v[98:99], off
	s_waitcnt vmcnt(8)
	s_waitcnt lgkmcnt(0)
	s_barrier
; #define PG8_STAGE(bufoff, gbase, voff) do { _Pragma("unroll") for (int _i = 0; _i < 2; ++_i) \
;         __builtin_amdgcn_global_load_lds((const unsigned*)((const char*)(gbase) + (voff)[_i]), (LAS unsigned*)(lds + (bufoff) + ldsw + _i * 8192), 16, 0, 0); } while (0)
; #define PG8_LDA(dst, b, h) do { _Pragma("unroll") for (int m = 0; m < 4; ++m) _Pragma("unroll") for (int k = 0; k < 2; ++k) dst[m][k] = *(const LAS bf16x8*)(lds + PG8_SA(b, h) + aoff + m * 2048 + k * 1024); } while (0)
; #define PG8_LDB(dst, b, h) do { _Pragma("unroll") for (int n = 0; n < 2; ++n) _Pragma("unroll") for (int k = 0; k < 2; ++k) dst[n][k] = *(const LAS bf16x8*)(lds + PG8_SB(b, h) + boff + n * 2048 + k * 1024); } while (0)
; #define PG8_MMA(ai, bj, At, Bt) do { __builtin_amdgcn_s_setprio(1); _Pragma("unroll") for (int m = 0; m < 4; ++m) _Pragma("unroll") for (int n = 0; n < 2; ++n) _Pragma("unroll") for (int k = 0; k < 2; ++k) \
;         acc[ai][bj][m][n] = __builtin_amdgcn_mfma_f32_16x16x32_bf16(Bt[n][k], At[m][k], acc[ai][bj][m][n], 0, 0, 0); __builtin_amdgcn_s_setprio(0); } while (0)
; template <class Epi, class Sched, bool HALFN = false>
; __device__ __forceinline__ void gemm_phase(LAS unsigned char* lds, const Gemm g, const Sched& S, const Epi& E, int wave_s) {
;     ...
;             PG8_LDB(B0, 0, 0); if (!HALFN) PG8_LDB(B1, 0, 1); PG8_SCHED; PG8_LDA(At, 0, 0); PG8_STAGE(PG8_SA(1, 1), a1 + hstep, voffA);
;             PG8_WAIT_V(8); PG8_WAIT_L(0); PG8_BAR; PG8_MMA(0, 0, At, B0); if (!HALFN) PG8_MMA(0, 1, At, B1); PG8_BAR; PG8_SCHED;
;             PG8_LDA(At, 0, 1); PG8_STAGE(PG8_SB(0, 0), b2, voffB); PG8_STAGE(PG8_SB(0, 1), b2 + bh1, voffB); PG8_STAGE(PG8_SA(0, 0), a2, voffA);
;             PG8_WAIT_V(8); PG8_WAIT_L(0); PG8_BAR; PG8_MMA(1, 0, At, B0); if (!HALFN) PG8_MMA(1, 1, At, B1); PG8_BAR; PG8_SCHED;
;             PG8_LDB(B0, 1, 0); if (!HALFN) PG8_LDB(B1, 1, 1); PG8_SCHED; PG8_LDA(At, 1, 0); PG8_STAGE(PG8_SA(0, 1), a2 + hstep, voffA);
;             PG8_WAIT_V(8); PG8_WAIT_L(0); PG8_BAR; PG8_MMA(0, 0, At, B0); if (!HALFN) PG8_MMA(0, 1, At, B1); PG8_BAR; PG8_SCHED;
;             PG8_LDA(At, 1, 1); PG8_STAGE(PG8_SB(1, 0), b3, voffB); PG8_STAGE(PG8_SB(1, 1), b3 + bh1, voffB); PG8_STAGE(PG8_SA(1, 0), a3, voffA);
;             PG8_WAIT_V(8); PG8_WAIT_L(0); PG8_BAR; PG8_MMA(1, 0, At, B0); if (!HALFN) PG8_MMA(1, 1, At, B1); PG8_BAR; PG8_SCHED;
	s_setprio 1
	s_waitcnt lgkmcnt(0)
	v_mfma_f32_16x16x32_bf16 v[82:85], v[190:193], v[208:211], v[82:85]
	v_mfma_f32_16x16x32_bf16 v[46:49], v[54:57], v[236:239], v[46:49]
	v_mfma_f32_16x16x32_bf16 v[50:53], v[190:193], v[236:239], v[50:53]
	v_mfma_f32_16x16x32_bf16 v[212:215], v[54:57], v[208:211], v[212:215]
	v_mfma_f32_16x16x32_bf16 v[82:85], v[194:197], v[216:219], v[82:85]
	v_mfma_f32_16x16x32_bf16 v[170:173], v[54:57], v[220:223], v[170:173]
	v_mfma_f32_16x16x32_bf16 v[178:181], v[190:193], v[220:223], v[178:181]
	v_mfma_f32_16x16x32_bf16 v[182:185], v[54:57], v[228:231], v[182:185]
	v_mfma_f32_16x16x32_bf16 v[186:189], v[190:193], v[228:231], v[186:189]
	v_mfma_f32_16x16x32_bf16 v[46:49], v[58:61], v[240:243], v[46:49]
	v_mfma_f32_16x16x32_bf16 v[50:53], v[194:197], v[240:243], v[50:53]
	v_mfma_f32_16x16x32_bf16 v[212:215], v[58:61], v[216:219], v[212:215]
	v_mfma_f32_16x16x32_bf16 v[170:173], v[58:61], v[224:227], v[170:173]
	v_mfma_f32_16x16x32_bf16 v[178:181], v[194:197], v[224:227], v[178:181]
	v_mfma_f32_16x16x32_bf16 v[182:185], v[58:61], v[232:235], v[182:185]
	v_mfma_f32_16x16x32_bf16 v[186:189], v[194:197], v[232:235], v[186:189]
	s_setprio 0
	s_barrier
	ds_read_b128 v[54:57], v44
	ds_read_b128 v[58:61], v44 offset:1024
	ds_read_b128 v[190:193], v44 offset:2048
	ds_read_b128 v[194:197], v44 offset:3072
	s_add_u32 s74, s34, 0x20280
	s_addc_u32 s75, s35, 0
	s_mov_b32 m0, s52
	v_lshl_add_u64 v[98:99], s[74:75], 0, v[100:101]
	ds_read_b128 v[208:211], v176
	ds_read_b128 v[216:219], v176 offset:1024
	ds_read_b128 v[220:223], v176 offset:2048
	ds_read_b128 v[224:227], v176 offset:3072
	ds_read_b128 v[228:231], v176 offset:4096
	ds_read_b128 v[232:235], v176 offset:5120
	ds_read_b128 v[236:239], v176 offset:6144
	ds_read_b128 v[240:243], v176 offset:7168
	global_load_lds_dwordx4 v[98:99], off
	v_lshl_add_u64 v[98:99], s[74:75], 0, v[102:103]
	s_mov_b32 m0, s21
	s_nop 0
	global_load_lds_dwordx4 v[98:99], off
	s_waitcnt vmcnt(8)
	s_waitcnt lgkmcnt(0)
	s_barrier
	s_setprio 1
	s_waitcnt lgkmcnt(0)
	v_mfma_f32_16x16x32_bf16 v[86:89], v[54:57], v[208:211], v[86:89]
	v_mfma_f32_16x16x32_bf16 v[90:93], v[190:193], v[208:211], v[90:93]
	v_mfma_f32_16x16x32_bf16 v[94:97], v[54:57], v[220:223], v[94:97]
	v_mfma_f32_16x16x32_bf16 v[62:65], v[190:193], v[220:223], v[62:65]
	v_mfma_f32_16x16x32_bf16 v[66:69], v[54:57], v[228:231], v[66:69]
	v_mfma_f32_16x16x32_bf16 v[70:73], v[190:193], v[228:231], v[70:73]
	v_mfma_f32_16x16x32_bf16 v[74:77], v[54:57], v[236:239], v[74:77]
	v_mfma_f32_16x16x32_bf16 v[78:81], v[190:193], v[236:239], v[78:81]
	v_mfma_f32_16x16x32_bf16 v[86:89], v[58:61], v[216:219], v[86:89]
	v_mfma_f32_16x16x32_bf16 v[90:93], v[194:197], v[216:219], v[90:93]
	v_mfma_f32_16x16x32_bf16 v[94:97], v[58:61], v[224:227], v[94:97]
	v_mfma_f32_16x16x32_bf16 v[62:65], v[194:197], v[224:227], v[62:65]
	v_mfma_f32_16x16x32_bf16 v[66:69], v[58:61], v[232:235], v[66:69]
	v_mfma_f32_16x16x32_bf16 v[70:73], v[194:197], v[232:235], v[70:73]
	v_mfma_f32_16x16x32_bf16 v[74:77], v[58:61], v[240:243], v[74:77]
	v_mfma_f32_16x16x32_bf16 v[78:81], v[194:197], v[240:243], v[78:81]
	s_setprio 0
	s_barrier
	s_mov_b64 s[74:75], 0x300
	s_mov_b32 m0, s48
	v_lshl_add_u64 v[98:99], v[36:37], 0, s[74:75]
	ds_read_b128 v[208:211], v176 offset:16384
	ds_read_b128 v[216:219], v176 offset:17408
	ds_read_b128 v[220:223], v176 offset:18432
	ds_read_b128 v[224:227], v176 offset:19456
	ds_read_b128 v[228:231], v176 offset:20480
	ds_read_b128 v[232:235], v176 offset:21504
	ds_read_b128 v[236:239], v176 offset:22528
	ds_read_b128 v[240:243], v176 offset:23552
	global_load_lds_dwordx4 v[98:99], off
	v_lshl_add_u64 v[174:175], v[38:39], 0, s[74:75]
	s_mov_b32 m0, s23
	s_nop 0
	global_load_lds_dwordx4 v[174:175], off
	s_mov_b32 m0, s47
	s_nop 0
	global_load_lds_dwordx4 v[98:99], off
	s_mov_b32 m0, s55
	v_lshl_add_u64 v[98:99], v[40:41], 0, s[74:75]
	global_load_lds_dwordx4 v[174:175], off
	s_mov_b32 m0, s31
	s_nop 0
	global_load_lds_dwordx4 v[98:99], off
	v_lshl_add_u64 v[98:99], v[42:43], 0, s[74:75]
	s_mov_b32 m0, s56
	s_nop 0
	global_load_lds_dwordx4 v[98:99], off
	s_waitcnt vmcnt(8)
	s_waitcnt lgkmcnt(0)
	s_barrier
	s_setprio 1
	s_waitcnt lgkmcnt(0)
	v_mfma_f32_16x16x32_bf16 v[82:85], v[190:193], v[208:211], v[82:85]
	v_mfma_f32_16x16x32_bf16 v[46:49], v[54:57], v[236:239], v[46:49]
	v_mfma_f32_16x16x32_bf16 v[50:53], v[190:193], v[236:239], v[50:53]
	v_mfma_f32_16x16x32_bf16 v[212:215], v[54:57], v[208:211], v[212:215]
	v_mfma_f32_16x16x32_bf16 v[82:85], v[194:197], v[216:219], v[82:85]
	v_mfma_f32_16x16x32_bf16 v[170:173], v[54:57], v[220:223], v[170:173]
	v_mfma_f32_16x16x32_bf16 v[178:181], v[190:193], v[220:223], v[178:181]
	v_mfma_f32_16x16x32_bf16 v[182:185], v[54:57], v[228:231], v[182:185]
	v_mfma_f32_16x16x32_bf16 v[186:189], v[190:193], v[228:231], v[186:189]
	v_mfma_f32_16x16x32_bf16 v[46:49], v[58:61], v[240:243], v[46:49]
	v_mfma_f32_16x16x32_bf16 v[50:53], v[194:197], v[240:243], v[50:53]
	v_mfma_f32_16x16x32_bf16 v[212:215], v[58:61], v[216:219], v[212:215]
	v_mfma_f32_16x16x32_bf16 v[170:173], v[58:61], v[224:227], v[170:173]
	v_mfma_f32_16x16x32_bf16 v[178:181], v[194:197], v[224:227], v[178:181]
	v_mfma_f32_16x16x32_bf16 v[182:185], v[58:61], v[232:235], v[182:185]
	v_mfma_f32_16x16x32_bf16 v[186:189], v[194:197], v[232:235], v[186:189]
	s_setprio 0
	s_barrier
; #define PG8_STAGE(bufoff, gbase, voff) do { _Pragma("unroll") for (int _i = 0; _i < 2; ++_i) \
;         __builtin_amdgcn_global_load_lds((const unsigned*)((const char*)(gbase) + (voff)[_i]), (LAS unsigned*)(lds + (bufoff) + ldsw + _i * 8192), 16, 0, 0); } while (0)
; #define PG8_LDA(dst, b, h) do { _Pragma("unroll") for (int m = 0; m < 4; ++m) _Pragma("unroll") for (int k = 0; k < 2; ++k) dst[m][k] = *(const LAS bf16x8*)(lds + PG8_SA(b, h) + aoff + m * 2048 + k * 1024); } while (0)
; #define PG8_LDB(dst, b, h) do { _Pragma("unroll") for (int n = 0; n < 2; ++n) _Pragma("unroll") for (int k = 0; k < 2; ++k) dst[n][k] = *(const LAS bf16x8*)(lds + PG8_SB(b, h) + boff + n * 2048 + k * 1024); } while (0)
; #define PG8_MMA(ai, bj, At, Bt) do { __builtin_amdgcn_s_setprio(1); _Pragma("unroll") for (int m = 0; m < 4; ++m) _Pragma("unroll") for (int n = 0; n < 2; ++n) _Pragma("unroll") for (int k = 0; k < 2; ++k) \
;         acc[ai][bj][m][n] = __builtin_amdgcn_mfma_f32_16x16x32_bf16(Bt[n][k], At[m][k], acc[ai][bj][m][n], 0, 0, 0); __builtin_amdgcn_s_setprio(0); } while (0)
; template <class Epi, class Sched, bool HALFN = false>
; __device__ __forceinline__ void gemm_phase(LAS unsigned char* lds, const Gemm g, const Sched& S, const Epi& E, int wave_s) {
;     ...
;             PG8_LDB(B0, 0, 0); if (!HALFN) PG8_LDB(B1, 0, 1); PG8_SCHED; PG8_LDA(At, 0, 0); PG8_STAGE(PG8_SA(1, 1), a1 + hstep, voffA);
;             PG8_WAIT_V(8); PG8_WAIT_L(0); PG8_BAR; PG8_MMA(0, 0, At, B0); if (!HALFN) PG8_MMA(0, 1, At, B1); PG8_BAR; PG8_SCHED;
;             PG8_LDA(At, 0, 1); PG8_STAGE(PG8_SB(0, 0), b2, voffB); PG8_STAGE(PG8_SB(0, 1), b2 + bh1, voffB); PG8_STAGE(PG8_SA(0, 0), a2, voffA);
;             PG8_WAIT_V(8); PG8_WAIT_L(0); PG8_BAR; PG8_MMA(1, 0, At, B0); if (!HALFN) PG8_MMA(1, 1, At, B1); PG8_BAR; PG8_SCHED;
;             PG8_LDB(B0, 1, 0); if (!HALFN) PG8_LDB(B1, 1, 1); PG8_SCHED; PG8_LDA(At, 1, 0); PG8_STAGE(PG8_SA(0, 1), a2 + hstep, voffA);
;             PG8_WAIT_V(8); PG8_WAIT_L(0); PG8_BAR; PG8_MMA(0, 0, At, B0); if (!HALFN) PG8_MMA(0, 1, At, B1); PG8_BAR; PG8_SCHED;
;             PG8_LDA(At, 1, 1); PG8_STAGE(PG8_SB(1, 0), b3, voffB); PG8_STAGE(PG8_SB(1, 1), b3 + bh1, voffB); PG8_STAGE(PG8_SA(1, 0), a3, voffA);
;             PG8_WAIT_V(8); PG8_WAIT_L(0); PG8_BAR; PG8_MMA(1, 0, At, B0); if (!HALFN) PG8_MMA(1, 1, At, B1); PG8_BAR; PG8_SCHED;
	ds_read_b128 v[54:57], v45
	ds_read_b128 v[58:61], v45 offset:1024
	ds_read_b128 v[190:193], v45 offset:2048
	ds_read_b128 v[194:197], v45 offset:3072
	s_add_u32 s74, s34, 0x20300
	s_addc_u32 s75, s35, 0
	s_mov_b32 m0, s57
	v_lshl_add_u64 v[98:99], s[74:75], 0, v[100:101]
	ds_read_b128 v[208:211], v176 offset:32768
	ds_read_b128 v[216:219], v176 offset:33792
	ds_read_b128 v[220:223], v176 offset:34816
	ds_read_b128 v[224:227], v176 offset:35840
	ds_read_b128 v[228:231], v176 offset:36864
	ds_read_b128 v[232:235], v176 offset:37888
	ds_read_b128 v[236:239], v176 offset:38912
	ds_read_b128 v[240:243], v176 offset:39936
	global_load_lds_dwordx4 v[98:99], off
	v_lshl_add_u64 v[98:99], s[74:75], 0, v[102:103]
	s_mov_b32 m0, s58
	s_nop 0
	global_load_lds_dwordx4 v[98:99], off
	s_waitcnt vmcnt(8)
	s_waitcnt lgkmcnt(0)
	s_barrier
	s_setprio 1
	s_waitcnt lgkmcnt(0)
	v_mfma_f32_16x16x32_bf16 v[86:89], v[54:57], v[208:211], v[86:89]
	v_mfma_f32_16x16x32_bf16 v[90:93], v[190:193], v[208:211], v[90:93]
	v_mfma_f32_16x16x32_bf16 v[94:97], v[54:57], v[220:223], v[94:97]
	v_mfma_f32_16x16x32_bf16 v[62:65], v[190:193], v[220:223], v[62:65]
	v_mfma_f32_16x16x32_bf16 v[66:69], v[54:57], v[228:231], v[66:69]
	v_mfma_f32_16x16x32_bf16 v[70:73], v[190:193], v[228:231], v[70:73]
	v_mfma_f32_16x16x32_bf16 v[74:77], v[54:57], v[236:239], v[74:77]
	v_mfma_f32_16x16x32_bf16 v[78:81], v[190:193], v[236:239], v[78:81]
	v_mfma_f32_16x16x32_bf16 v[86:89], v[58:61], v[216:219], v[86:89]
	v_mfma_f32_16x16x32_bf16 v[90:93], v[194:197], v[216:219], v[90:93]
	v_mfma_f32_16x16x32_bf16 v[94:97], v[58:61], v[224:227], v[94:97]
	v_mfma_f32_16x16x32_bf16 v[62:65], v[194:197], v[224:227], v[62:65]
	v_mfma_f32_16x16x32_bf16 v[66:69], v[58:61], v[232:235], v[66:69]
	v_mfma_f32_16x16x32_bf16 v[70:73], v[194:197], v[232:235], v[70:73]
	v_mfma_f32_16x16x32_bf16 v[74:77], v[58:61], v[240:243], v[74:77]
	v_mfma_f32_16x16x32_bf16 v[78:81], v[194:197], v[240:243], v[78:81]
	s_setprio 0
	s_barrier
	s_mov_b64 s[74:75], 0x380
	s_mov_b32 m0, s36
	v_lshl_add_u64 v[36:37], v[36:37], 0, s[74:75]
	ds_read_b128 v[208:211], v176 offset:49152
	ds_read_b128 v[216:219], v176 offset:50176
	ds_read_b128 v[220:223], v176 offset:51200
	ds_read_b128 v[224:227], v176 offset:52224
	ds_read_b128 v[228:231], v176 offset:53248
	ds_read_b128 v[232:235], v176 offset:54272
	ds_read_b128 v[236:239], v176 offset:55296
	ds_read_b128 v[240:243], v176 offset:56320
	global_load_lds_dwordx4 v[36:37], off
	v_lshl_add_u64 v[38:39], v[38:39], 0, s[74:75]
	s_mov_b32 m0, s29
	s_nop 0
	global_load_lds_dwordx4 v[38:39], off
	s_mov_b32 m0, s64
	s_nop 0
	global_load_lds_dwordx4 v[36:37], off
	s_mov_b32 m0, s65
	v_lshl_add_u64 v[36:37], v[40:41], 0, s[74:75]
	global_load_lds_dwordx4 v[38:39], off
	s_mov_b32 m0, s59
	s_nop 0
	global_load_lds_dwordx4 v[36:37], off
	v_lshl_add_u64 v[36:37], v[42:43], 0, s[74:75]
	s_mov_b32 m0, s62
	s_nop 0
	global_load_lds_dwordx4 v[36:37], off
	s_waitcnt vmcnt(8)
	s_waitcnt lgkmcnt(0)
	s_barrier
	s_setprio 1
	s_waitcnt lgkmcnt(0)
	v_mfma_f32_16x16x32_bf16 v[36:39], v[54:57], v[208:211], v[212:215]
	v_mfma_f32_16x16x32_bf16 v[40:43], v[190:193], v[208:211], v[82:85]
	v_mfma_f32_16x16x32_bf16 v[82:85], v[54:57], v[220:223], v[170:173]
	v_mfma_f32_16x16x32_bf16 v[46:49], v[54:57], v[236:239], v[46:49]
	v_mfma_f32_16x16x32_bf16 v[50:53], v[190:193], v[236:239], v[50:53]
	v_mfma_f32_16x16x32_bf16 v[36:39], v[58:61], v[216:219], v[36:39]
	v_mfma_f32_16x16x32_bf16 v[40:43], v[194:197], v[216:219], v[40:43]
	v_mfma_f32_16x16x32_bf16 v[82:85], v[58:61], v[224:227], v[82:85]
	v_mfma_f32_16x16x32_bf16 v[170:173], v[190:193], v[220:223], v[178:181]
	v_mfma_f32_16x16x32_bf16 v[178:181], v[54:57], v[228:231], v[182:185]
	v_mfma_f32_16x16x32_bf16 v[182:185], v[190:193], v[228:231], v[186:189]
	v_mfma_f32_16x16x32_bf16 v[46:49], v[58:61], v[240:243], v[46:49]
	v_mfma_f32_16x16x32_bf16 v[50:53], v[194:197], v[240:243], v[50:53]
	v_mfma_f32_16x16x32_bf16 v[170:173], v[194:197], v[224:227], v[170:173]
	v_mfma_f32_16x16x32_bf16 v[178:181], v[58:61], v[232:235], v[178:181]
	v_mfma_f32_16x16x32_bf16 v[182:185], v[194:197], v[232:235], v[182:185]
	s_setprio 0
	s_barrier
	ds_read_b128 v[54:57], v44
	ds_read_b128 v[58:61], v44 offset:1024
	ds_read_b128 v[186:189], v44 offset:2048
	ds_read_b128 v[190:193], v44 offset:3072
	s_add_u32 s34, s34, 0x20380
	s_addc_u32 s35, s35, 0
	s_mov_b32 m0, s52
	v_lshl_add_u64 v[98:99], s[34:35], 0, v[100:101]
	ds_read_b128 v[194:197], v176
	ds_read_b128 v[208:211], v176 offset:1024
	ds_read_b128 v[212:215], v176 offset:2048
	ds_read_b128 v[216:219], v176 offset:3072
	ds_read_b128 v[220:223], v176 offset:4096
	ds_read_b128 v[224:227], v176 offset:5120
	ds_read_b128 v[228:231], v176 offset:6144
	ds_read_b128 v[232:235], v176 offset:7168
	global_load_lds_dwordx4 v[98:99], off
	v_lshl_add_u64 v[98:99], s[34:35], 0, v[102:103]
	s_mov_b32 m0, s21
	s_nop 0
	global_load_lds_dwordx4 v[98:99], off
	s_waitcnt vmcnt(8)
	s_waitcnt lgkmcnt(0)
	s_barrier
	s_setprio 1
	s_waitcnt lgkmcnt(0)
	v_mfma_f32_16x16x32_bf16 v[86:89], v[54:57], v[194:197], v[86:89]
	v_mfma_f32_16x16x32_bf16 v[90:93], v[186:189], v[194:197], v[90:93]
	v_mfma_f32_16x16x32_bf16 v[62:65], v[186:189], v[212:215], v[62:65]
	v_mfma_f32_16x16x32_bf16 v[66:69], v[54:57], v[220:223], v[66:69]
	v_mfma_f32_16x16x32_bf16 v[70:73], v[186:189], v[220:223], v[70:73]
	v_mfma_f32_16x16x32_bf16 v[74:77], v[54:57], v[228:231], v[74:77]
	v_mfma_f32_16x16x32_bf16 v[86:89], v[58:61], v[208:211], v[86:89]
	v_mfma_f32_16x16x32_bf16 v[90:93], v[190:193], v[208:211], v[90:93]
	v_mfma_f32_16x16x32_bf16 v[94:97], v[54:57], v[212:215], v[94:97]
	v_mfma_f32_16x16x32_bf16 v[62:65], v[190:193], v[216:219], v[62:65]
	v_mfma_f32_16x16x32_bf16 v[66:69], v[58:61], v[224:227], v[66:69]
	v_mfma_f32_16x16x32_bf16 v[70:73], v[190:193], v[224:227], v[70:73]
	v_mfma_f32_16x16x32_bf16 v[208:211], v[58:61], v[232:235], v[74:77]
	v_mfma_f32_16x16x32_bf16 v[74:77], v[186:189], v[228:231], v[78:81]
	v_mfma_f32_16x16x32_bf16 v[194:197], v[58:61], v[216:219], v[94:97]
	v_mfma_f32_16x16x32_bf16 v[212:215], v[190:193], v[232:235], v[74:77]
	s_setprio 0
	s_barrier
; #define PG8_STAGE(bufoff, gbase, voff) do { _Pragma("unroll") for (int _i = 0; _i < 2; ++_i) \
;         __builtin_amdgcn_global_load_lds((const unsigned*)((const char*)(gbase) + (voff)[_i]), (LAS unsigned*)(lds + (bufoff) + ldsw + _i * 8192), 16, 0, 0); } while (0)
; #define PG8_WAIT_V(n) asm volatile("s_waitcnt vmcnt(" #n ")" ::: "memory")
; #define PG8_WAIT_L(n) asm volatile("s_waitcnt lgkmcnt(" #n ")" ::: "memory")
; #define PG8_BAR __builtin_amdgcn_s_barrier()
; template <class Epi, class Sched, bool HALFN = false>
; __device__ __forceinline__ void gemm_phase(LAS unsigned char* lds, const Gemm g, const Sched& S, const Epi& E, int wave_s) {
;     ...
;         const char* nA = has_next ? (const char*)g.A + (size_t)nxt.z * g.zA * 2 + (size_t)nxt.pm * tstep : cA; const char* nB = has_next ? (const char*)g.Bt + (size_t)nxt.z * g.zB * 2 + (size_t)nxt.pn * (HALFN ? hstep : tstep) : cB;
;         for (int t = 0; t < nt; t += 2) {
;             const bool last = (t == nt - 2);
;             const char* a1 = cA + (size_t)(t + 1) * kstep;
;             const char* a2 = last ? nA : cA + (size_t)(t + 2) * kstep; const char* b2 = last ? nB : cB + (size_t)(t + 2) * kstep;
;             const char* a3 = a2 + kstep; const char* b3 = b2 + kstep;
;             PG8_LDB(B0, 0, 0); if (!HALFN) PG8_LDB(B1, 0, 1); PG8_SCHED; PG8_LDA(At, 0, 0); PG8_STAGE(PG8_SA(1, 1), a1 + hstep, voffA);
;             PG8_WAIT_V(8); PG8_WAIT_L(0); PG8_BAR; PG8_MMA(0, 0, At, B0); if (!HALFN) PG8_MMA(0, 1, At, B1); PG8_BAR; PG8_SCHED;
;             PG8_LDA(At, 0, 1); PG8_STAGE(PG8_SB(0, 0), b2, voffB); PG8_STAGE(PG8_SB(0, 1), b2 + bh1, voffB); PG8_STAGE(PG8_SA(0, 0), a2, voffA);
;             PG8_WAIT_V(8); PG8_WAIT_L(0); PG8_BAR; PG8_MMA(1, 0, At, B0); if (!HALFN) PG8_MMA(1, 1, At, B1); PG8_BAR; PG8_SCHED;
;             PG8_LDB(B0, 1, 0); if (!HALFN) PG8_LDB(B1, 1, 1); PG8_SCHED; PG8_LDA(At, 1, 0); PG8_STAGE(PG8_SA(0, 1), a2 + hstep, voffA);
;             PG8_WAIT_V(8); PG8_WAIT_L(0); PG8_BAR; PG8_MMA(0, 0, At, B0); if (!HALFN) PG8_MMA(0, 1, At, B1); PG8_BAR; PG8_SCHED;
;             PG8_LDA(At, 1, 1); PG8_STAGE(PG8_SB(1, 0), b3, voffB); PG8_STAGE(PG8_SB(1, 1), b3 + bh1, voffB); PG8_STAGE(PG8_SA(1, 0), a3, voffA);
;             PG8_WAIT_V(8); PG8_WAIT_L(0); PG8_BAR; PG8_MMA(1, 0, At, B0); if (!HALFN) PG8_MMA(1, 1, At, B1); PG8_BAR; PG8_SCHED;
;         }
;         if (wr == 0) PG8_BAR;
	s_mov_b32 m0, s48
	v_lshl_add_u64 v[174:175], s[4:5], 0, v[18:19]
	s_nop 1
	ds_read_b128 v[74:77], v176 offset:16384
	ds_read_b128 v[78:81], v176 offset:17408
	ds_read_b128 v[94:97], v176 offset:18432
	ds_read_b128 v[216:219], v176 offset:19456
	ds_read_b128 v[220:223], v176 offset:20480
	ds_read_b128 v[224:227], v176 offset:21504
	ds_read_b128 v[228:231], v176 offset:22528
	ds_read_b128 v[232:235], v176 offset:23552
	global_load_lds_dwordx4 v[174:175], off
	v_lshl_add_u64 v[198:199], s[4:5], 0, v[104:105]
	s_mov_b32 m0, s23
	v_lshl_add_u64 v[202:203], s[24:25], 0, v[100:101]
	global_load_lds_dwordx4 v[198:199], off
	s_mov_b32 m0, s47
	v_lshl_add_u64 v[248:249], s[24:25], 0, v[102:103]
	global_load_lds_dwordx4 v[174:175], off
	s_mov_b32 m0, s55
	s_nop 0
	global_load_lds_dwordx4 v[198:199], off
	s_mov_b32 m0, s31
	s_nop 0
	global_load_lds_dwordx4 v[202:203], off
	s_mov_b32 m0, s56
	s_nop 0
	global_load_lds_dwordx4 v[248:249], off
	s_waitcnt vmcnt(8)
	s_waitcnt lgkmcnt(0)
	s_barrier
	s_setprio 1
	s_waitcnt lgkmcnt(0)
	v_mfma_f32_16x16x32_bf16 v[36:39], v[54:57], v[74:77], v[36:39]
	v_mfma_f32_16x16x32_bf16 v[40:43], v[186:189], v[74:77], v[40:43]
	v_mfma_f32_16x16x32_bf16 v[74:77], v[54:57], v[94:97], v[82:85]
	v_mfma_f32_16x16x32_bf16 v[236:239], v[58:61], v[216:219], v[74:77]
	v_mfma_f32_16x16x32_bf16 v[74:77], v[186:189], v[94:97], v[170:173]
	v_mfma_f32_16x16x32_bf16 v[170:173], v[190:193], v[216:219], v[74:77]
	v_mfma_f32_16x16x32_bf16 v[74:77], v[54:57], v[220:223], v[178:181]
	v_mfma_f32_16x16x32_bf16 v[46:49], v[54:57], v[228:231], v[46:49]
	v_mfma_f32_16x16x32_bf16 v[36:39], v[58:61], v[78:81], v[36:39]
	v_mfma_f32_16x16x32_bf16 v[40:43], v[190:193], v[78:81], v[40:43]
	v_mfma_f32_16x16x32_bf16 v[178:181], v[58:61], v[224:227], v[74:77]
	v_mfma_f32_16x16x32_bf16 v[74:77], v[186:189], v[220:223], v[182:185]
	v_mfma_f32_16x16x32_bf16 v[216:219], v[58:61], v[232:235], v[46:49]
	v_mfma_f32_16x16x32_bf16 v[46:49], v[186:189], v[228:231], v[50:53]
	v_mfma_f32_16x16x32_bf16 v[182:185], v[190:193], v[224:227], v[74:77]
	v_mfma_f32_16x16x32_bf16 v[186:189], v[190:193], v[232:235], v[46:49]
	s_setprio 0
	s_barrier
	ds_read_b128 v[190:193], v45
	ds_read_b128 v[220:223], v45 offset:1024
	ds_read_b128 v[224:227], v45 offset:2048
	ds_read_b128 v[228:231], v45 offset:3072
	s_add_u32 s4, s24, 0x20000
	s_addc_u32 s5, s25, 0
	s_mov_b32 m0, s57
	v_lshl_add_u64 v[60:61], s[4:5], 0, v[100:101]
	ds_read_b128 v[44:47], v176 offset:32768
	ds_read_b128 v[48:51], v176 offset:33792
	ds_read_b128 v[52:55], v176 offset:34816
	ds_read_b128 v[56:59], v176 offset:35840
	ds_read_b128 v[74:77], v176 offset:36864
	ds_read_b128 v[232:235], v176 offset:37888
	ds_read_b128 v[240:243], v176 offset:38912
	ds_read_b128 v[244:247], v176 offset:39936
	global_load_lds_dwordx4 v[60:61], off
	v_lshl_add_u64 v[60:61], s[4:5], 0, v[102:103]
	s_mov_b32 m0, s58
	s_nop 0
	global_load_lds_dwordx4 v[60:61], off
	s_waitcnt vmcnt(8)
	s_waitcnt lgkmcnt(0)
	s_barrier
	s_setprio 1
	s_waitcnt lgkmcnt(0)
	v_mfma_f32_16x16x32_bf16 v[78:81], v[190:193], v[44:47], v[86:89]
	v_mfma_f32_16x16x32_bf16 v[44:47], v[224:227], v[44:47], v[90:93]
	v_mfma_f32_16x16x32_bf16 v[92:95], v[228:231], v[48:51], v[44:47]
	v_mfma_f32_16x16x32_bf16 v[44:47], v[190:193], v[52:55], v[194:197]
	v_mfma_f32_16x16x32_bf16 v[88:91], v[220:223], v[56:59], v[44:47]
	v_mfma_f32_16x16x32_bf16 v[44:47], v[224:227], v[52:55], v[62:65]
	v_mfma_f32_16x16x32_bf16 v[84:87], v[228:231], v[56:59], v[44:47]
	v_mfma_f32_16x16x32_bf16 v[44:47], v[190:193], v[74:77], v[66:69]
	v_mfma_f32_16x16x32_bf16 v[96:99], v[220:223], v[48:51], v[78:81]
	v_mfma_f32_16x16x32_bf16 v[80:83], v[220:223], v[232:235], v[44:47]
	v_mfma_f32_16x16x32_bf16 v[44:47], v[224:227], v[74:77], v[70:73]
	v_mfma_f32_16x16x32_bf16 v[76:79], v[228:231], v[232:235], v[44:47]
	v_mfma_f32_16x16x32_bf16 v[44:47], v[190:193], v[240:243], v[208:211]
	v_mfma_f32_16x16x32_bf16 v[72:75], v[220:223], v[244:247], v[44:47]
	v_mfma_f32_16x16x32_bf16 v[44:47], v[224:227], v[240:243], v[212:215]
	v_mfma_f32_16x16x32_bf16 v[68:71], v[228:231], v[244:247], v[44:47]
	s_setprio 0
	s_barrier
	s_mov_b32 m0, s36
	v_lshl_add_u64 v[56:57], v[174:175], 0, s[50:51]
	s_nop 2
	ds_read_b128 v[44:47], v176 offset:49152
	ds_read_b128 v[48:51], v176 offset:50176
	ds_read_b128 v[52:55], v176 offset:51200
	ds_read_b128 v[194:197], v176 offset:52224
	ds_read_b128 v[208:211], v176 offset:53248
	ds_read_b128 v[212:215], v176 offset:54272
	ds_read_b128 v[232:235], v176 offset:55296
	ds_read_b128 v[240:243], v176 offset:56320
	global_load_lds_dwordx4 v[56:57], off
	v_lshl_add_u64 v[58:59], v[198:199], 0, s[50:51]
	s_mov_b32 m0, s29
	s_nop 0
	global_load_lds_dwordx4 v[58:59], off
	s_mov_b32 m0, s64
	s_nop 0
	global_load_lds_dwordx4 v[56:57], off
	s_mov_b32 m0, s65
	v_lshl_add_u64 v[56:57], v[202:203], 0, s[50:51]
	global_load_lds_dwordx4 v[58:59], off
	s_mov_b32 m0, s59
	s_nop 0
	global_load_lds_dwordx4 v[56:57], off
	v_lshl_add_u64 v[56:57], v[248:249], 0, s[50:51]
	s_mov_b32 m0, s62
	s_nop 0
	global_load_lds_dwordx4 v[56:57], off
	s_waitcnt vmcnt(8)
	s_waitcnt lgkmcnt(0)
	s_barrier
	s_setprio 1
	s_waitcnt lgkmcnt(0)
	v_mfma_f32_16x16x32_bf16 v[36:39], v[190:193], v[44:47], v[36:39]
	v_mfma_f32_16x16x32_bf16 v[64:67], v[220:223], v[48:51], v[36:39]
	v_mfma_f32_16x16x32_bf16 v[36:39], v[224:227], v[44:47], v[40:43]
	v_mfma_f32_16x16x32_bf16 v[60:63], v[228:231], v[48:51], v[36:39]
	v_mfma_f32_16x16x32_bf16 v[36:39], v[190:193], v[52:55], v[236:239]
	v_mfma_f32_16x16x32_bf16 v[56:59], v[220:223], v[194:197], v[36:39]
	v_mfma_f32_16x16x32_bf16 v[36:39], v[224:227], v[52:55], v[170:173]
	v_mfma_f32_16x16x32_bf16 v[52:55], v[228:231], v[194:197], v[36:39]
	v_mfma_f32_16x16x32_bf16 v[36:39], v[190:193], v[208:211], v[178:181]
	v_mfma_f32_16x16x32_bf16 v[48:51], v[220:223], v[212:215], v[36:39]
	v_mfma_f32_16x16x32_bf16 v[36:39], v[224:227], v[208:211], v[182:185]
	v_mfma_f32_16x16x32_bf16 v[44:47], v[228:231], v[212:215], v[36:39]
	v_mfma_f32_16x16x32_bf16 v[36:39], v[190:193], v[232:235], v[216:219]
	v_mfma_f32_16x16x32_bf16 v[40:43], v[220:223], v[240:243], v[36:39]
	v_mfma_f32_16x16x32_bf16 v[36:39], v[224:227], v[232:235], v[186:189]
	v_mfma_f32_16x16x32_bf16 v[36:39], v[228:231], v[240:243], v[36:39]
	s_setprio 0
	s_barrier
	s_andn2_b64 vcc, exec, s[18:19]
	s_cbranch_vccnz .LBB0_892
	s_barrier
